# in-projection epilogue tables (bias row, ssq rows, gains) fetched by LDS-DMA into spare LDS at tile start, read from LDS after the K-loop
# speedup vs baseline: 1.0908x; 1.0036x over previous
; template <bool F16>
; DI void gemm256(const bf16_t* __restrict__ A, const bf16_t* __restrict__ Bt, int brow, int bcol, char* ldsc,
;                 f32x4 (&acc)[2][2][4][2]) {
;     ...
;   const int wid = tid >> 6, lane = tid & 63, wr = wid >> 2, wc = wid & 3, fr = lane & 15, fq = lane >> 4;
;   bf16x8 At[4][2], B0[2][2], B1[2][2];
;   constexpr int nt = K / G_BK;
;   unsigned voff[2];
; #pragma unroll
;   for (int i = 0; i < 2; ++i) { int r_, c_; stage_rc(tid * 16 + i * 8192, r_, c_); voff[i] = (unsigned)((r_ * K + c_) * 2); }
;   STAGE(SB(0, 0), Bt, bcol, 0); STAGE(SB(0, 1), Bt, bcol + G_HALF, 0); STAGE(SA(0, 0), A, brow, 0); STAGE(SA(0, 1), A, brow + G_HALF, 0);
; DI void phaseA_tile(const Params& p0, int l, int ft, int mt, char* lds) {
;     ...
;     const float* bb = p.bias + (size_t)(l * 17 + modrow) * INW + n0 + wr * 64 + fq * 4;
; #pragma unroll
;     for (int ai = 0; ai < 2; ++ai)
; #pragma unroll
;       for (int m = 0; m < 4; ++m) bvA[ai][m] = *(const f32x4*)(bb + ai * 128 + m * 16);
;   }
;   float rstd[4];
; #pragma unroll
;   for (int gp = 0; gp < 2; ++gp) {
;     f32x4 sq[2][4];
; #pragma unroll
;     for (int n = 0; n < 2; ++n) {
;       const f32x4* sp = (const f32x4*)(p.ssq + (size_t)(m0 + tl[gp * 2 + n]) * 16);
; #pragma unroll
;       for (int q = 0; q < 4; ++q) sq[n][q] = sp[q];
;     }
; #pragma unroll
;     for (int n = 0; n < 2; ++n) {
;       float ss = 0.f;
; #pragma unroll
;       for (int q = 0; q < 4; ++q) ss += (sq[n][q][0] + sq[n][q][1]) + (sq[n][q][2] + sq[n][q][3]);
;       rstd[gp * 2 + n] = rsqrtf(ss * (1.f / DM) + EPS);
;     }
;   }
; #pragma unroll
;   for (int ai = 0; ai < 2; ++ai) {
;     const int f0 = n0 + ai * 128 + wr * 64;
;     const int hd = f0 >> 6;
;     int kind = 0; const float* gain = p.att_q_gain; bool do_rope = false; bool do_scale = false;
;     bf16_t* vtb = nullptr;
;     if (hd < 8) { kind = 2; gain = p.att_q_gain + l * 64; do_rope = !is_ctx; do_scale = true; }
;     else if (hd < 10) { kind = 2; gain = p.att_k_gain + l * 64; do_rope = !is_ctx; }
;     else if (hd < 12) { kind = 3; vtb = p.VtA + (size_t)((b * 2 + (hd - 10)) * 64) * KEYS; }
;     else if (hd < 20) { kind = 1; }
;     else if (hd < 24) { kind = 0; }
;     else if (hd < 28) { kind = 1; }
;     else if (hd < 32) { kind = 2; gain = p.na_q_gain + l * 64; do_scale = true; }
;     else if (hd < 36) { kind = 2; gain = p.na_k_gain + l * 64; }
.LBB0_350:
	v_readlane_b32 s29, v255, 3
	s_load_dwordx2 s[30:31], s[80:81], 0xd0
	s_load_dwordx2 s[34:35], s[80:81], 0xe8
	s_lshr_b32 s69, s28, 3
	s_cmpk_lt_i32 s28, 0x80
	s_cselect_b32 s69, s69, 16
	s_mul_i32 s70, s29, 17
	s_add_i32 s69, s69, s70
	s_mul_hi_u32 s70, s69, 0x2c00
	s_mul_i32 s69, s69, 0x2c00
	s_lshl_b32 s71, s68, 10
	s_add_u32 s69, s69, s71
	s_addc_u32 s70, s70, 0
	v_lshlrev_b32_e32 v226, 4, v240
	v_lshrrev_b32_e32 v228, 6, v251
	v_lshl_add_u32 v227, v228, 11, v226
	s_nop 0
	v_readfirstlane_b32 s74, v228
	s_nop 3
	s_lshl_b32 s74, s74, 11
	s_waitcnt lgkmcnt(0)
	s_add_u32 s30, s30, s69
	s_addc_u32 s31, s31, s70
	s_lshl_b32 s69, s28, 14
	s_add_u32 s34, s34, s69
	s_addc_u32 s35, s35, 0
	s_mov_b32 m0, 0x21e40
	s_nop 0
	global_load_lds_dwordx4 v226, s[30:31]
	s_add_u32 m0, s74, 0x22340
	s_nop 0
	global_load_lds_dwordx4 v227, s[34:35]
	global_load_lds_dwordx4 v227, s[34:35] offset:1024
	s_lshl_b32 s69, 1, s68
	s_movk_i32 s70, 0x40
	s_and_b32 s71, s69, 0x4
	s_cselect_b32 s70, 0x48, s70
	s_and_b32 s71, s69, 0x80
	s_cselect_b32 s70, 0x60, s70
	s_and_b32 s71, s69, 0x100
	s_cselect_b32 s70, 0x68, s70
	s_load_dwordx2 s[30:31], s[80:81], s70
	s_lshl_b32 s69, s29, 8
	s_waitcnt lgkmcnt(0)
	s_add_u32 s30, s30, s69
	s_addc_u32 s31, s31, 0
	s_mov_b64 s[34:35], exec
	s_mov_b64 exec, 0xffff
	s_mov_b32 m0, 0x22240
	s_nop 0
	global_load_lds_dwordx4 v226, s[30:31]
	s_mov_b64 exec, s[34:35]
	v_mov_b32_e32 v40, v251
	v_mov_b32_e32 v11, 1
	v_ashrrev_i32_e32 v0, 31, v40
	v_lshrrev_b32_e32 v0, 26, v0
	v_add_u32_e32 v0, v40, v0
	v_ashrrev_i32_e32 v2, 6, v0
	v_bfe_i32 v0, v40, 27, 1
	v_lshlrev_b32_e32 v41, 4, v40
	v_lshrrev_b32_e32 v0, 22, v0
	v_add_u32_e32 v0, v41, v0
	v_and_b32_e32 v0, 0xfffffc00, v0
	v_sub_u32_e32 v0, v41, v0
	v_lshrrev_b32_e32 v3, 4, v0
	v_bitop3_b32 v4, v3, v0, 32 bitop3:0x6c
	v_ashrrev_i32_e32 v0, 31, v0
	v_lshrrev_b32_e32 v0, 26, v0
	v_lshlrev_b32_e32 v3, 3, v2
	v_add_u32_e32 v0, v4, v0
	v_and_b32_e32 v5, 0x1ffff0, v3
	v_ashrrev_i32_e32 v3, 6, v0
	v_mul_i32_i24_e32 v6, 64, v3
	v_sub_u32_e32 v4, v4, v6
	v_lshlrev_b32_e32 v0, 5, v2
	v_ashrrev_i16_sdwa v4, v11, sext(v4) dst_sel:DWORD dst_unused:UNUSED_PAD src0_sel:DWORD src1_sel:BYTE_0
	v_and_b32_e32 v0, 32, v0
	v_bfe_i32 v4, v4, 0, 16
	v_add_u32_e32 v0, v0, v4
	v_add_lshl_u32 v5, v3, v5, 11
	v_add_u32_e32 v42, 0x2000, v41
	v_lshl_add_u32 v0, v0, 1, v5
	v_ashrrev_i32_e32 v5, 31, v42
	v_lshrrev_b32_e32 v5, 22, v5
	v_add_u32_e32 v5, v42, v5
	v_ashrrev_i32_e32 v5, 10, v5
	v_mul_i32_i24_e32 v6, 0x400, v5
	v_sub_u32_e32 v6, v42, v6
	s_lshl_b32 s2, s28, 8
	v_lshrrev_b32_e32 v7, 4, v6
	v_bitop3_b32 v7, v7, v6, 32 bitop3:0x6c
	v_lshlrev_b32_e32 v6, 3, v5
	s_ashr_i32 s3, s2, 31
	v_readlane_b32 s36, v254, 41
	s_lshl_b32 s10, s68, 8
	v_and_b32_e32 v8, 0x1ffff0, v6
	v_ashrrev_i32_e32 v6, 31, v7
	s_lshl_b64 s[4:5], s[2:3], 11
	v_readlane_b32 s42, v254, 47
	v_lshrrev_b32_e32 v6, 26, v6
	v_readlane_b32 s43, v254, 48
	s_add_u32 s4, s42, s4
	v_add_u32_e32 v9, v7, v6
	s_addc_u32 s5, s43, s5
	s_bitset1_b32 s2, 7
	v_ashrrev_i32_e32 v6, 6, v9
	v_and_b32_e32 v9, 0xc0, v9
	s_ashr_i32 s3, s2, 31
	v_sub_u32_e32 v7, v7, v9
	s_lshl_b64 s[2:3], s[2:3], 11
	v_lshlrev_b32_e32 v10, 5, v5
	v_ashrrev_i16_sdwa v7, v11, sext(v7) dst_sel:DWORD dst_unused:UNUSED_PAD src0_sel:DWORD src1_sel:BYTE_0
	v_add_u32_e32 v43, 0x10000, v41
	s_add_u32 s6, s42, s2
	v_and_b32_e32 v10, 32, v10
	v_bfe_i32 v7, v7, 0, 16
	v_readfirstlane_b32 s0, v43
	v_add_u32_e32 v44, 0x12000, v41
	s_addc_u32 s7, s43, s3
	s_ashr_i32 s11, s10, 31
	v_add_u32_e32 v9, v10, v7
	v_add_lshl_u32 v8, v6, v8, 11
	s_mov_b32 m0, s0
	v_readfirstlane_b32 s0, v44
	v_add_u32_e32 v45, 0x14000, v41
	s_lshl_b64 s[12:13], s[10:11], 11
	v_lshl_add_u32 v34, v9, 1, v8
	global_load_lds_dwordx4 v0, s[4:5]
	s_mov_b32 m0, s0
	v_readfirstlane_b32 s0, v45
	v_add_u32_e32 v46, 0x16000, v41
	s_add_u32 s8, s27, s12
	global_load_lds_dwordx4 v34, s[4:5]
	s_mov_b32 m0, s0
	v_readfirstlane_b32 s0, v46
	s_addc_u32 s9, s61, s13
	s_or_b32 s2, s10, 0x80
	global_load_lds_dwordx4 v0, s[6:7]
	s_mov_b32 m0, s0
	v_readfirstlane_b32 s0, v41
	s_ashr_i32 s3, s2, 31
	global_load_lds_dwordx4 v34, s[6:7]
	s_mov_b32 m0, s0
	v_readfirstlane_b32 s0, v42
	s_lshl_b64 s[2:3], s[2:3], 11
	v_add_u32_e32 v47, 0x4000, v41
	global_load_lds_dwordx4 v0, s[8:9]
	s_mov_b32 m0, s0
	s_add_u32 s10, s27, s2
	v_readfirstlane_b32 s0, v47
	v_add_u32_e32 v48, 0x6000, v41
	global_load_lds_dwordx4 v34, s[8:9]
	s_addc_u32 s11, s61, s3
	s_mov_b32 m0, s0
	v_readfirstlane_b32 s0, v48
	global_load_lds_dwordx4 v0, s[10:11]
	s_mov_b32 m0, s0
	v_ashrrev_i32_e32 v8, 8, v40
	global_load_lds_dwordx4 v34, s[10:11]
	v_cmp_eq_u32_e32 vcc, 1, v8
	v_readlane_b32 s37, v254, 42
	v_readlane_b32 s38, v254, 43
	v_readlane_b32 s39, v254, 44
	v_readlane_b32 s40, v254, 45
	v_readlane_b32 s41, v254, 46
	v_readlane_b32 s44, v254, 49
	v_readlane_b32 s45, v254, 50
	v_readlane_b32 s46, v254, 51
	v_readlane_b32 s47, v254, 52
	v_readlane_b32 s48, v254, 53
	v_readlane_b32 s49, v254, 54
	v_readlane_b32 s50, v254, 55
	v_readlane_b32 s51, v254, 56
	s_and_saveexec_b64 s[2:3], vcc
	s_cbranch_execz .LBB0_352
	s_barrier

; DI int get_tid() { int t = threadIdx.x; asm volatile("" : "+v"(t)); return t; }
; DI void phaseA_tile(const Params& p0, int l, int ft, int mt, char* lds) {
;     ...
;   const int n0 = ft * 256, m0 = mt * 256;
;   const int tid = get_tid(), lane = tid & 63, wid = tid >> 6, wr = wid >> 2, wc = wid & 3, fr = lane & 15, fq = lane >> 4;
;   const bool is_ctx = m0 >= NLAT;
;   int b, s_base, modrow;
;   if (!is_ctx) { b = m0 / SEQ; s_base = m0 % SEQ; modrow = b; }
;   else { const int c = m0 - NLAT; b = c / CTX; s_base = c % CTX; modrow = 16; }
;   int tl[4];
; #pragma unroll
;   for (int g = 0; g < 4; ++g) tl[g] = (g >> 1) * 128 + wc * 32 + (g & 1) * 16 + fr;
;   f32x4 bvA[2][4];
;   {
;     const float* bb = p.bias + (size_t)(l * 17 + modrow) * INW + n0 + wr * 64 + fq * 4;
; #pragma unroll
;     for (int ai = 0; ai < 2; ++ai)
; #pragma unroll
;       for (int m = 0; m < 4; ++m) bvA[ai][m] = *(const f32x4*)(bb + ai * 128 + m * 16);
;   }
;   float rstd[4];
; #pragma unroll
;   for (int gp = 0; gp < 2; ++gp) {
;     f32x4 sq[2][4];
; #pragma unroll
;     for (int n = 0; n < 2; ++n) {
;       const f32x4* sp = (const f32x4*)(p.ssq + (size_t)(m0 + tl[gp * 2 + n]) * 16);
; #pragma unroll
;       for (int q = 0; q < 4; ++q) sq[n][q] = sp[q];
;     }
; #pragma unroll
;     for (int n = 0; n < 2; ++n) {
;       float ss = 0.f;
; #pragma unroll
;       for (int q = 0; q < 4; ++q) ss += (sq[n][q][0] + sq[n][q][1]) + (sq[n][q][2] + sq[n][q][3]);
;       rstd[gp * 2 + n] = rsqrtf(ss * (1.f / DM) + EPS);
;     }
;   }
.LBB0_356:
	s_or_b64 exec, exec, s[2:3]
	v_readlane_b32 s38, v255, 3
	s_barrier
	s_load_dwordx2 s[34:35], s[80:81], 0xb8
	s_load_dwordx4 s[8:11], s[80:81], 0xa8
	s_load_dwordx2 s[6:7], s[80:81], 0xd8
	s_lshl_b32 s0, s28, 8
	s_lshl_b32 s30, s68, 8
	s_lshr_b32 s2, s28, 3
	s_sub_i32 s3, s28, 0x80
	s_and_b32 s69, s28, 7
	s_lshl_b32 s69, s69, 8
	s_cmpk_lt_i32 s28, 0x80
	s_cselect_b32 s39, s2, s3
	s_cselect_b32 s2, s2, 16
	s_cselect_b32 s69, s69, 0
	s_cselect_b32 s74, 0, 0x800
	s_cselect_b32 s42, 1, 0
	s_lshl_b32 s3, 1, s68
	s_mov_b32 s40, 1
	s_mov_b32 s41, 1
	s_and_b32 s70, s3, 0x187
	s_cselect_b32 s40, 2, s40
	s_and_b32 s70, s3, 0x200
	s_cselect_b32 s40, 3, s40
	s_and_b32 s70, s3, 0x20
	s_cselect_b32 s40, 0, s40
	s_and_b32 s70, s3, 0x183
	s_cselect_b32 s41, 2, s41
	s_and_b32 s70, s3, 0x204
	s_cselect_b32 s41, 3, s41
	s_and_b32 s70, s3, 0x20
	s_cselect_b32 s41, 0, s41
	s_and_b32 s70, s3, 0x7
	s_cselect_b32 s42, s42, 0
	s_mov_b32 s43, 1.0
	s_and_b32 s70, s3, 0x83
	s_cselect_b32 s43, 0x3e38aa3b, s43
	s_waitcnt lgkmcnt(0)
	s_lshl_b32 s2, s69, 1
	s_add_u32 s46, s6, s2
	s_addc_u32 s47, s7, 0
	v_and_b32_e32 v114, 15, v251
	v_bfe_u32 v115, v251, 4, 2
	v_bfe_u32 v116, v251, 6, 2
	v_lshrrev_b32_e32 v117, 8, v251
	v_lshlrev_b32_e32 v140, 4, v115
	v_lshl_add_u32 v137, v117, 8, v140
	v_add_u32_e32 v137, 0x21e40, v137
	v_lshl_add_u32 v118, v116, 5, v114
	v_lshl_add_u32 v138, v118, 6, v140
	v_add_u32_e32 v138, 0x22340, v138
	v_add_u32_e32 v140, 0x22240, v140
	v_lshrrev_b32_e32 v119, 1, v116
	v_lshlrev_b32_e32 v120, 5, v115
	v_lshl_add_u32 v141, v119, 7, v120
	v_and_b32_e32 v119, 1, v116
	v_lshl_add_u32 v119, v119, 5, v114
	v_lshl_add_u32 v142, v119, 7, v120
	v_lshrrev_b32_e32 v119, 1, v115
	v_lshl_or_b32 v119, v117, 3, v119
	v_xor_b32_e32 v119, v119, v114
	v_lshlrev_b32_e32 v119, 4, v119
	v_and_b32_e32 v120, 1, v115
	v_lshl_or_b32 v119, v120, 3, v119
	v_lshl_add_u32 v130, v118, 9, v119
	v_xor_b32_e32 v131, 32, v130
	v_xor_b32_e32 v132, 64, v130
	v_xor_b32_e32 v133, 96, v130
	v_and_b32_e32 v119, 3, v114
	v_and_b32_e32 v120, 4, v114
	v_lshl_or_b32 v119, v120, 1, v119
	v_and_b32_e32 v120, 8, v114
	v_lshrrev_b32_e32 v120, 1, v120
	v_or_b32_e32 v119, v119, v120
	v_lshl_add_u32 v119, v116, 5, v119
	v_lshlrev_b32_e32 v119, 1, v119
	v_mul_u32_u24_e32 v120, 0x4800, v115
	v_mul_u32_u24_e32 v121, 0x48000, v117
	v_add3_u32 v134, v119, v120, v121
	v_xor_b32_e32 v135, 16, v240
	v_lshlrev_b32_e32 v135, 2, v135
	v_xor_b32_e32 v136, 32, v240
	v_lshlrev_b32_e32 v136, 2, v136
	ds_read_b128 v[34:37], v137 offset:0
	ds_read_b128 v[38:41], v137 offset:64
	ds_read_b128 v[42:45], v137 offset:128
	ds_read_b128 v[46:49], v137 offset:192
	ds_read_b128 v[146:149], v137 offset:512
	ds_read_b128 v[150:153], v137 offset:576
	ds_read_b128 v[154:157], v137 offset:640
	ds_read_b128 v[158:161], v137 offset:704
	ds_read_b128 v[114:117], v138 offset:0
	ds_read_b128 v[118:121], v138 offset:1024
	ds_read_b128 v[122:125], v138 offset:8192
	ds_read_b128 v[126:129], v138 offset:9216
	ds_read_b128 v[194:197], v140
	ds_read_b128 v[198:201], v140 offset:64
	ds_read_b128 v[202:205], v140 offset:128
	ds_read_b128 v[206:209], v140 offset:192
	global_load_dwordx4 v[210:213], v141, s[46:47] offset:0
	global_load_dwordx4 v[214:217], v141, s[46:47] offset:16
	global_load_dwordx4 v[218:221], v141, s[46:47] offset:256
	global_load_dwordx4 v[222:225], v141, s[46:47] offset:272
	global_load_dwordx4 v[226:229], v142, s[6:7] offset:0
	global_load_dwordx4 v[230:233], v142, s[6:7] offset:16
	global_load_dwordx4 v[234:237], v142, s[6:7] offset:2048
	global_load_dwordx4 v[242:245], v142, s[6:7] offset:2064
	s_waitcnt lgkmcnt(0)
	v_add_f32_e32 v114, v114, v115
	v_add_f32_e32 v116, v116, v117
	v_add_f32_e32 v118, v118, v119
	v_add_f32_e32 v120, v120, v121
	v_add_f32_e32 v122, v122, v123
	v_add_f32_e32 v124, v124, v125
	v_add_f32_e32 v126, v126, v127
	v_add_f32_e32 v128, v128, v129
	v_add_f32_e32 v143, v114, v116
	v_add_f32_e32 v144, v118, v120
	v_add_f32_e32 v145, v122, v124
	v_add_f32_e32 v239, v126, v128
	ds_bpermute_b32 v114, v135, v143
	ds_bpermute_b32 v115, v135, v144
	ds_bpermute_b32 v116, v135, v145
	ds_bpermute_b32 v117, v135, v239
	s_waitcnt lgkmcnt(0)
	v_add_f32_e32 v143, v143, v114
	v_add_f32_e32 v144, v144, v115
	v_add_f32_e32 v145, v145, v116
	v_add_f32_e32 v239, v239, v117
	ds_bpermute_b32 v114, v136, v143
	ds_bpermute_b32 v115, v136, v144
	ds_bpermute_b32 v116, v136, v145
	ds_bpermute_b32 v117, v136, v239
	s_waitcnt lgkmcnt(0)
	v_add_f32_e32 v143, v143, v114
	v_add_f32_e32 v144, v144, v115
	v_add_f32_e32 v145, v145, v116
	v_add_f32_e32 v239, v239, v117
	v_mov_b32_e32 v118, 0x358637bd
	s_mov_b32 s2, 0x3a800000
	s_mov_b32 s3, 0x800000
	v_fma_f32 v143, v143, s2, v118
	v_fma_f32 v144, v144, s2, v118
	v_fma_f32 v145, v145, s2, v118
	v_fma_f32 v239, v239, s2, v118
	v_mul_f32_e32 v119, 0x4b800000, v143
	v_cmp_gt_f32_e32 vcc, s3, v143
	s_nop 1
	v_cndmask_b32_e32 v119, v143, v119, vcc
	v_rsq_f32_e32 v119, v119
	s_nop 0
	v_mul_f32_e32 v0, 0x45800000, v119
	v_cndmask_b32_e32 v0, v119, v0, vcc
	v_mul_f32_e32 v120, 0x4b800000, v144
	v_cmp_gt_f32_e32 vcc, s3, v144
	s_nop 1
	v_cndmask_b32_e32 v120, v144, v120, vcc
	v_rsq_f32_e32 v120, v120
	s_nop 0
	v_mul_f32_e32 v238, 0x45800000, v120
	v_cndmask_b32_e32 v238, v120, v238, vcc
	v_mul_f32_e32 v121, 0x4b800000, v145
	v_cmp_gt_f32_e32 vcc, s3, v145
	s_nop 1
	v_cndmask_b32_e32 v121, v145, v121, vcc
	v_rsq_f32_e32 v121, v121
	s_nop 0
	v_mul_f32_e32 v246, 0x45800000, v121
	v_cndmask_b32_e32 v246, v121, v246, vcc
	v_mul_f32_e32 v122, 0x4b800000, v239
	v_cmp_gt_f32_e32 vcc, s3, v239
	s_nop 1
	v_cndmask_b32_e32 v122, v239, v122, vcc
	v_rsq_f32_e32 v122, v122
	s_nop 0
	v_mul_f32_e32 v248, 0x45800000, v122
	v_cndmask_b32_e32 v248, v122, v248, vcc
	s_mov_b32 s70, 0xbfb8aa3b
	s_mov_b32 s71, 1.0
	v_pk_fma_f32 v[190:191], v[190:191], v[0:1], v[34:35] op_sel_hi:[1,0,1]
	v_pk_fma_f32 v[192:193], v[192:193], v[0:1], v[36:37] op_sel_hi:[1,0,1]
	v_pk_fma_f32 v[186:187], v[186:187], v[0:1], v[38:39] op_sel_hi:[1,0,1]
	v_pk_fma_f32 v[188:189], v[188:189], v[0:1], v[40:41] op_sel_hi:[1,0,1]
	v_pk_fma_f32 v[178:179], v[178:179], v[0:1], v[42:43] op_sel_hi:[1,0,1]
	v_pk_fma_f32 v[180:181], v[180:181], v[0:1], v[44:45] op_sel_hi:[1,0,1]
	v_pk_fma_f32 v[170:171], v[170:171], v[0:1], v[46:47] op_sel_hi:[1,0,1]
	v_pk_fma_f32 v[172:173], v[172:173], v[0:1], v[48:49] op_sel_hi:[1,0,1]
	v_pk_fma_f32 v[182:183], v[182:183], v[238:239], v[34:35] op_sel_hi:[1,0,1]
	v_pk_fma_f32 v[184:185], v[184:185], v[238:239], v[36:37] op_sel_hi:[1,0,1]
	v_pk_fma_f32 v[174:175], v[174:175], v[238:239], v[38:39] op_sel_hi:[1,0,1]
	v_pk_fma_f32 v[176:177], v[176:177], v[238:239], v[40:41] op_sel_hi:[1,0,1]
	v_pk_fma_f32 v[166:167], v[166:167], v[238:239], v[42:43] op_sel_hi:[1,0,1]
	v_pk_fma_f32 v[168:169], v[168:169], v[238:239], v[44:45] op_sel_hi:[1,0,1]
	v_pk_fma_f32 v[162:163], v[162:163], v[238:239], v[46:47] op_sel_hi:[1,0,1]
	v_pk_fma_f32 v[164:165], v[164:165], v[238:239], v[48:49] op_sel_hi:[1,0,1]
	s_cmp_eq_u32 s40, 1
	s_cbranch_scc0 .Lea_n1_00
; DI float silu_f(float v) { return v * __builtin_amdgcn_rcpf(1.f + __expf(-v)); }
; DI void phaseA_tile(const Params& p0, int l, int ft, int mt, char* lds) {
;     ...
;       if (kind == 1) {
; #pragma unroll
;         for (int n = 0; n < 2; ++n)
; #pragma unroll
;           for (int m = 0; m < 4; ++m)
; #pragma unroll
;             for (int j = 0; j < 4; ++j) v[n][m][j] = silu_f(v[n][m][j]);
	v_pk_mul_f32 v[114:115], v[190:191], s[70:71] op_sel_hi:[1,0]
	v_pk_mul_f32 v[116:117], v[192:193], s[70:71] op_sel_hi:[1,0]
	v_pk_mul_f32 v[118:119], v[186:187], s[70:71] op_sel_hi:[1,0]
	v_pk_mul_f32 v[120:121], v[188:189], s[70:71] op_sel_hi:[1,0]
	v_exp_f32_e32 v114, v114
	v_exp_f32_e32 v115, v115
	v_exp_f32_e32 v116, v116
	v_exp_f32_e32 v117, v117
	v_exp_f32_e32 v118, v118
	v_exp_f32_e32 v119, v119
	v_exp_f32_e32 v120, v120
	v_exp_f32_e32 v121, v121
	v_pk_add_f32 v[114:115], v[114:115], s[70:71] op_sel:[0,1] op_sel_hi:[1,1]
	v_pk_add_f32 v[116:117], v[116:117], s[70:71] op_sel:[0,1] op_sel_hi:[1,1]
	v_pk_add_f32 v[118:119], v[118:119], s[70:71] op_sel:[0,1] op_sel_hi:[1,1]
	v_pk_add_f32 v[120:121], v[120:121], s[70:71] op_sel:[0,1] op_sel_hi:[1,1]
	v_rcp_f32_e32 v114, v114
	v_rcp_f32_e32 v115, v115
	v_rcp_f32_e32 v116, v116
	v_rcp_f32_e32 v117, v117
	v_rcp_f32_e32 v118, v118
	v_rcp_f32_e32 v119, v119
	v_rcp_f32_e32 v120, v120
	v_rcp_f32_e32 v121, v121
	s_nop 0
	v_pk_mul_f32 v[190:191], v[190:191], v[114:115]
	v_pk_mul_f32 v[192:193], v[192:193], v[116:117]
	v_pk_mul_f32 v[186:187], v[186:187], v[118:119]
	v_pk_mul_f32 v[188:189], v[188:189], v[120:121]
	v_pk_mul_f32 v[114:115], v[178:179], s[70:71] op_sel_hi:[1,0]
	v_pk_mul_f32 v[116:117], v[180:181], s[70:71] op_sel_hi:[1,0]
	v_pk_mul_f32 v[118:119], v[170:171], s[70:71] op_sel_hi:[1,0]
	v_pk_mul_f32 v[120:121], v[172:173], s[70:71] op_sel_hi:[1,0]
	v_exp_f32_e32 v114, v114
	v_exp_f32_e32 v115, v115
	v_exp_f32_e32 v116, v116
	v_exp_f32_e32 v117, v117
	v_exp_f32_e32 v118, v118
	v_exp_f32_e32 v119, v119
	v_exp_f32_e32 v120, v120
	v_exp_f32_e32 v121, v121
	v_pk_add_f32 v[114:115], v[114:115], s[70:71] op_sel:[0,1] op_sel_hi:[1,1]
	v_pk_add_f32 v[116:117], v[116:117], s[70:71] op_sel:[0,1] op_sel_hi:[1,1]
	v_pk_add_f32 v[118:119], v[118:119], s[70:71] op_sel:[0,1] op_sel_hi:[1,1]
	v_pk_add_f32 v[120:121], v[120:121], s[70:71] op_sel:[0,1] op_sel_hi:[1,1]
	v_rcp_f32_e32 v114, v114
	v_rcp_f32_e32 v115, v115
	v_rcp_f32_e32 v116, v116
	v_rcp_f32_e32 v117, v117
	v_rcp_f32_e32 v118, v118
	v_rcp_f32_e32 v119, v119
	v_rcp_f32_e32 v120, v120
	v_rcp_f32_e32 v121, v121
	s_nop 0
	v_pk_mul_f32 v[178:179], v[178:179], v[114:115]
	v_pk_mul_f32 v[180:181], v[180:181], v[116:117]
	v_pk_mul_f32 v[170:171], v[170:171], v[118:119]
	v_pk_mul_f32 v[172:173], v[172:173], v[120:121]
	v_pk_mul_f32 v[114:115], v[182:183], s[70:71] op_sel_hi:[1,0]
	v_pk_mul_f32 v[116:117], v[184:185], s[70:71] op_sel_hi:[1,0]
	v_pk_mul_f32 v[118:119], v[174:175], s[70:71] op_sel_hi:[1,0]
	v_pk_mul_f32 v[120:121], v[176:177], s[70:71] op_sel_hi:[1,0]
	v_exp_f32_e32 v114, v114
	v_exp_f32_e32 v115, v115
	v_exp_f32_e32 v116, v116
	v_exp_f32_e32 v117, v117
	v_exp_f32_e32 v118, v118
	v_exp_f32_e32 v119, v119
	v_exp_f32_e32 v120, v120
	v_exp_f32_e32 v121, v121
	v_pk_add_f32 v[114:115], v[114:115], s[70:71] op_sel:[0,1] op_sel_hi:[1,1]
	v_pk_add_f32 v[116:117], v[116:117], s[70:71] op_sel:[0,1] op_sel_hi:[1,1]
	v_pk_add_f32 v[118:119], v[118:119], s[70:71] op_sel:[0,1] op_sel_hi:[1,1]
	v_pk_add_f32 v[120:121], v[120:121], s[70:71] op_sel:[0,1] op_sel_hi:[1,1]
	v_rcp_f32_e32 v114, v114
	v_rcp_f32_e32 v115, v115
	v_rcp_f32_e32 v116, v116
	v_rcp_f32_e32 v117, v117
	v_rcp_f32_e32 v118, v118
	v_rcp_f32_e32 v119, v119
	v_rcp_f32_e32 v120, v120
	v_rcp_f32_e32 v121, v121
	s_nop 0
	v_pk_mul_f32 v[182:183], v[182:183], v[114:115]
	v_pk_mul_f32 v[184:185], v[184:185], v[116:117]
	v_pk_mul_f32 v[174:175], v[174:175], v[118:119]
	v_pk_mul_f32 v[176:177], v[176:177], v[120:121]
	v_pk_mul_f32 v[114:115], v[166:167], s[70:71] op_sel_hi:[1,0]
	v_pk_mul_f32 v[116:117], v[168:169], s[70:71] op_sel_hi:[1,0]
	v_pk_mul_f32 v[118:119], v[162:163], s[70:71] op_sel_hi:[1,0]
	v_pk_mul_f32 v[120:121], v[164:165], s[70:71] op_sel_hi:[1,0]
	v_exp_f32_e32 v114, v114
	v_exp_f32_e32 v115, v115
	v_exp_f32_e32 v116, v116
	v_exp_f32_e32 v117, v117
	v_exp_f32_e32 v118, v118
	v_exp_f32_e32 v119, v119
	v_exp_f32_e32 v120, v120
	v_exp_f32_e32 v121, v121
	v_pk_add_f32 v[114:115], v[114:115], s[70:71] op_sel:[0,1] op_sel_hi:[1,1]
	v_pk_add_f32 v[116:117], v[116:117], s[70:71] op_sel:[0,1] op_sel_hi:[1,1]
	v_pk_add_f32 v[118:119], v[118:119], s[70:71] op_sel:[0,1] op_sel_hi:[1,1]
	v_pk_add_f32 v[120:121], v[120:121], s[70:71] op_sel:[0,1] op_sel_hi:[1,1]
	v_rcp_f32_e32 v114, v114
	v_rcp_f32_e32 v115, v115
	v_rcp_f32_e32 v116, v116
	v_rcp_f32_e32 v117, v117
	v_rcp_f32_e32 v118, v118
	v_rcp_f32_e32 v119, v119
	v_rcp_f32_e32 v120, v120
	v_rcp_f32_e32 v121, v121
	s_nop 0
	v_pk_mul_f32 v[166:167], v[166:167], v[114:115]
	v_pk_mul_f32 v[168:169], v[168:169], v[116:117]
	v_pk_mul_f32 v[162:163], v[162:163], v[118:119]
	v_pk_mul_f32 v[164:165], v[164:165], v[120:121]
	s_branch .Lea_pack_00
; DI void phaseA_tile(const Params& p0, int l, int ft, int mt, char* lds) {
;     ...
;       } else if (kind == 2) {
;         f32x4 gv[4];
; #pragma unroll
;         for (int m = 0; m < 4; ++m) gv[m] = *(const f32x4*)(gain + m * 16 + fq * 4);
; #pragma unroll
;         for (int n = 0; n < 2; ++n) {
;           float ss = 0.f;
; #pragma unroll
;           for (int m = 0; m < 4; ++m)
; #pragma unroll
;             for (int j = 0; j < 4; ++j) ss += v[n][m][j] * v[n][m][j];
;           ss += __shfl_xor(ss, 16);
;           ss += __shfl_xor(ss, 32);
;           const float rn = rsqrtf(ss * (1.f / 64.f) + EPS) * sc;
; #pragma unroll
;           for (int m = 0; m < 4; ++m)
; #pragma unroll
;             for (int j = 0; j < 4; ++j) v[n][m][j] *= rn * gv[m][j];
.Lea_n1_00:
	s_cmp_eq_u32 s40, 2
	s_cbranch_scc0 .Lea_n2_00
	v_pk_mul_f32 v[114:115], v[190:191], v[190:191]
	v_pk_fma_f32 v[114:115], v[192:193], v[192:193], v[114:115]
	v_pk_fma_f32 v[114:115], v[186:187], v[186:187], v[114:115]
	v_pk_fma_f32 v[114:115], v[188:189], v[188:189], v[114:115]
	v_pk_fma_f32 v[114:115], v[178:179], v[178:179], v[114:115]
	v_pk_fma_f32 v[114:115], v[180:181], v[180:181], v[114:115]
	v_pk_fma_f32 v[114:115], v[170:171], v[170:171], v[114:115]
	v_pk_fma_f32 v[114:115], v[172:173], v[172:173], v[114:115]
	v_pk_mul_f32 v[116:117], v[182:183], v[182:183]
	v_pk_fma_f32 v[116:117], v[184:185], v[184:185], v[116:117]
	v_pk_fma_f32 v[116:117], v[174:175], v[174:175], v[116:117]
	v_pk_fma_f32 v[116:117], v[176:177], v[176:177], v[116:117]
	v_pk_fma_f32 v[116:117], v[166:167], v[166:167], v[116:117]
	v_pk_fma_f32 v[116:117], v[168:169], v[168:169], v[116:117]
	v_pk_fma_f32 v[116:117], v[162:163], v[162:163], v[116:117]
	v_pk_fma_f32 v[116:117], v[164:165], v[164:165], v[116:117]
	v_add_f32_e32 v114, v114, v115
	v_add_f32_e32 v116, v116, v117
	ds_bpermute_b32 v118, v135, v114
	ds_bpermute_b32 v119, v135, v116
	s_waitcnt lgkmcnt(0)
	v_add_f32_e32 v114, v114, v118
	v_add_f32_e32 v116, v116, v119
	ds_bpermute_b32 v118, v136, v114
	ds_bpermute_b32 v119, v136, v116
	s_waitcnt lgkmcnt(0)
	v_add_f32_e32 v114, v114, v118
	v_add_f32_e32 v116, v116, v119
	v_mov_b32_e32 v120, 0x358637bd
	s_mov_b32 s2, 0x3c800000
	v_fma_f32 v114, v114, s2, v120
	v_fma_f32 v116, v116, s2, v120
	v_mul_f32_e32 v118, 0x4b800000, v114
	v_cmp_gt_f32_e32 vcc, s3, v114
	s_nop 1
	v_cndmask_b32_e32 v118, v114, v118, vcc
	v_rsq_f32_e32 v118, v118
	s_nop 0
	v_mul_f32_e32 v122, 0x45800000, v118
	v_cndmask_b32_e32 v122, v118, v122, vcc
	v_mul_f32_e32 v119, 0x4b800000, v116
	v_cmp_gt_f32_e32 vcc, s3, v116
	s_nop 1
	v_cndmask_b32_e32 v119, v116, v119, vcc
	v_rsq_f32_e32 v119, v119
	s_nop 0
	v_mul_f32_e32 v124, 0x45800000, v119
	v_cndmask_b32_e32 v124, v119, v124, vcc
	v_mul_f32_e32 v122, s43, v122
	v_mul_f32_e32 v124, s43, v124
	v_pk_mul_f32 v[126:127], v[194:195], v[122:123] op_sel_hi:[1,0]
	v_pk_mul_f32 v[190:191], v[190:191], v[126:127]
	v_pk_mul_f32 v[126:127], v[196:197], v[122:123] op_sel_hi:[1,0]
	v_pk_mul_f32 v[192:193], v[192:193], v[126:127]
	v_pk_mul_f32 v[126:127], v[198:199], v[122:123] op_sel_hi:[1,0]
	v_pk_mul_f32 v[186:187], v[186:187], v[126:127]
	v_pk_mul_f32 v[126:127], v[200:201], v[122:123] op_sel_hi:[1,0]
	v_pk_mul_f32 v[188:189], v[188:189], v[126:127]
	v_pk_mul_f32 v[126:127], v[202:203], v[122:123] op_sel_hi:[1,0]
	v_pk_mul_f32 v[178:179], v[178:179], v[126:127]
	v_pk_mul_f32 v[126:127], v[204:205], v[122:123] op_sel_hi:[1,0]
	v_pk_mul_f32 v[180:181], v[180:181], v[126:127]
	v_pk_mul_f32 v[126:127], v[206:207], v[122:123] op_sel_hi:[1,0]
	v_pk_mul_f32 v[170:171], v[170:171], v[126:127]
	v_pk_mul_f32 v[126:127], v[208:209], v[122:123] op_sel_hi:[1,0]
	v_pk_mul_f32 v[172:173], v[172:173], v[126:127]
	v_pk_mul_f32 v[126:127], v[194:195], v[124:125] op_sel_hi:[1,0]
	v_pk_mul_f32 v[182:183], v[182:183], v[126:127]
	v_pk_mul_f32 v[126:127], v[196:197], v[124:125] op_sel_hi:[1,0]
	v_pk_mul_f32 v[184:185], v[184:185], v[126:127]
	v_pk_mul_f32 v[126:127], v[198:199], v[124:125] op_sel_hi:[1,0]
	v_pk_mul_f32 v[174:175], v[174:175], v[126:127]
	v_pk_mul_f32 v[126:127], v[200:201], v[124:125] op_sel_hi:[1,0]
	v_pk_mul_f32 v[176:177], v[176:177], v[126:127]
	v_pk_mul_f32 v[126:127], v[202:203], v[124:125] op_sel_hi:[1,0]
	v_pk_mul_f32 v[166:167], v[166:167], v[126:127]
	v_pk_mul_f32 v[126:127], v[204:205], v[124:125] op_sel_hi:[1,0]
	v_pk_mul_f32 v[168:169], v[168:169], v[126:127]
	v_pk_mul_f32 v[126:127], v[206:207], v[124:125] op_sel_hi:[1,0]
	v_pk_mul_f32 v[162:163], v[162:163], v[126:127]
	v_pk_mul_f32 v[126:127], v[208:209], v[124:125] op_sel_hi:[1,0]
	v_pk_mul_f32 v[164:165], v[164:165], v[126:127]
	s_cmp_eq_u32 s42, 0
	s_cbranch_scc1 .Lea_pack_00
	s_waitcnt vmcnt(0)
	v_mul_f32_e32 v126, v186, v211
	v_mul_f32_e32 v127, v190, v211
	v_fma_f32 v190, v190, v210, -v126
	v_fma_f32 v186, v186, v210, v127
	v_mul_f32_e32 v126, v187, v213
	v_mul_f32_e32 v127, v191, v213
	v_fma_f32 v191, v191, v212, -v126
	v_fma_f32 v187, v187, v212, v127
	v_mul_f32_e32 v126, v188, v215
	v_mul_f32_e32 v127, v192, v215
	v_fma_f32 v192, v192, v214, -v126
	v_fma_f32 v188, v188, v214, v127
	v_mul_f32_e32 v126, v189, v217
	v_mul_f32_e32 v127, v193, v217
	v_fma_f32 v193, v193, v216, -v126
	v_fma_f32 v189, v189, v216, v127
	v_mul_f32_e32 v126, v170, v227
	v_mul_f32_e32 v127, v178, v227
	v_fma_f32 v178, v178, v226, -v126
	v_fma_f32 v170, v170, v226, v127
	v_mul_f32_e32 v126, v171, v229
	v_mul_f32_e32 v127, v179, v229
	v_fma_f32 v179, v179, v228, -v126
	v_fma_f32 v171, v171, v228, v127
	v_mul_f32_e32 v126, v172, v231
	v_mul_f32_e32 v127, v180, v231
	v_fma_f32 v180, v180, v230, -v126
	v_fma_f32 v172, v172, v230, v127
	v_mul_f32_e32 v126, v173, v233
	v_mul_f32_e32 v127, v181, v233
	v_fma_f32 v181, v181, v232, -v126
	v_fma_f32 v173, v173, v232, v127
	v_mul_f32_e32 v126, v174, v211
	v_mul_f32_e32 v127, v182, v211
	v_fma_f32 v182, v182, v210, -v126
	v_fma_f32 v174, v174, v210, v127
	v_mul_f32_e32 v126, v175, v213
	v_mul_f32_e32 v127, v183, v213
	v_fma_f32 v183, v183, v212, -v126
	v_fma_f32 v175, v175, v212, v127
	v_mul_f32_e32 v126, v176, v215
	v_mul_f32_e32 v127, v184, v215
	v_fma_f32 v184, v184, v214, -v126
	v_fma_f32 v176, v176, v214, v127
	v_mul_f32_e32 v126, v177, v217
	v_mul_f32_e32 v127, v185, v217
	v_fma_f32 v185, v185, v216, -v126
	v_fma_f32 v177, v177, v216, v127
	v_mul_f32_e32 v126, v162, v235
	v_mul_f32_e32 v127, v166, v235
	v_fma_f32 v166, v166, v234, -v126
	v_fma_f32 v162, v162, v234, v127
	v_mul_f32_e32 v126, v163, v237
	v_mul_f32_e32 v127, v167, v237
	v_fma_f32 v167, v167, v236, -v126
	v_fma_f32 v163, v163, v236, v127
	v_mul_f32_e32 v126, v164, v243
	v_mul_f32_e32 v127, v168, v243
	v_fma_f32 v168, v168, v242, -v126
	v_fma_f32 v164, v164, v242, v127
	v_mul_f32_e32 v126, v165, v245
	v_mul_f32_e32 v127, v169, v245
	v_fma_f32 v169, v169, v244, -v126
	v_fma_f32 v165, v165, v244, v127
	s_branch .Lea_pack_00

; DI void phaseA_tile(const Params& p0, int l, int ft, int mt, char* lds) {
;     ...
;       } else if (kind == 2) {
;         f32x4 gv[4];
; #pragma unroll
;         for (int m = 0; m < 4; ++m) gv[m] = *(const f32x4*)(gain + m * 16 + fq * 4);
; #pragma unroll
;         for (int n = 0; n < 2; ++n) {
;           float ss = 0.f;
; #pragma unroll
;           for (int m = 0; m < 4; ++m)
; #pragma unroll
;             for (int j = 0; j < 4; ++j) ss += v[n][m][j] * v[n][m][j];
;           ss += __shfl_xor(ss, 16);
;           ss += __shfl_xor(ss, 32);
;           const float rn = rsqrtf(ss * (1.f / 64.f) + EPS) * sc;
; #pragma unroll
;           for (int m = 0; m < 4; ++m)
; #pragma unroll
;             for (int j = 0; j < 4; ++j) v[n][m][j] *= rn * gv[m][j];
;         }
;         if (do_rope) {
; #pragma unroll
;           for (int n = 0; n < 2; ++n) {
;             f32x4 cs4[2][2];
;             const int s = s_base + tl[gp * 2 + n];
; #pragma unroll
;             for (int hf = 0; hf < 2; ++hf) {
;               const int pos = hf == 0 ? (s >> 6) : (s & 63);
;               const float* tb = p.rope + (size_t)pos * 32 + fq * 8;
;               cs4[hf][0] = *(const f32x4*)(tb);
;               cs4[hf][1] = *(const f32x4*)(tb + 4);
;             }
; #pragma unroll
;             for (int hf = 0; hf < 2; ++hf)
; #pragma unroll
;               for (int j = 0; j < 4; ++j) {
;                 const float c = cs4[hf][j >> 1][(j & 1) * 2], sn = cs4[hf][j >> 1][(j & 1) * 2 + 1];
;                 const float x1 = v[n][2 * hf][j], x2 = v[n][2 * hf + 1][j];
;                 v[n][2 * hf][j] = x1 * c - x2 * sn;
;                 v[n][2 * hf + 1][j] = x2 * c + x1 * sn;
;               }
;           }
;         }
.Lea_n1_10:
	s_cmp_eq_u32 s41, 2
	s_cbranch_scc0 .Lea_n2_10
	v_pk_mul_f32 v[114:115], v[78:79], v[78:79]
	v_pk_fma_f32 v[114:115], v[80:81], v[80:81], v[114:115]
	v_pk_fma_f32 v[114:115], v[74:75], v[74:75], v[114:115]
	v_pk_fma_f32 v[114:115], v[76:77], v[76:77], v[114:115]
	v_pk_fma_f32 v[114:115], v[66:67], v[66:67], v[114:115]
	v_pk_fma_f32 v[114:115], v[68:69], v[68:69], v[114:115]
	v_pk_fma_f32 v[114:115], v[58:59], v[58:59], v[114:115]
	v_pk_fma_f32 v[114:115], v[60:61], v[60:61], v[114:115]
	v_pk_mul_f32 v[116:117], v[70:71], v[70:71]
	v_pk_fma_f32 v[116:117], v[72:73], v[72:73], v[116:117]
	v_pk_fma_f32 v[116:117], v[62:63], v[62:63], v[116:117]
	v_pk_fma_f32 v[116:117], v[64:65], v[64:65], v[116:117]
	v_pk_fma_f32 v[116:117], v[54:55], v[54:55], v[116:117]
	v_pk_fma_f32 v[116:117], v[56:57], v[56:57], v[116:117]
	v_pk_fma_f32 v[116:117], v[50:51], v[50:51], v[116:117]
	v_pk_fma_f32 v[116:117], v[52:53], v[52:53], v[116:117]
	v_add_f32_e32 v114, v114, v115
	v_add_f32_e32 v116, v116, v117
	ds_bpermute_b32 v118, v135, v114
	ds_bpermute_b32 v119, v135, v116
	s_waitcnt lgkmcnt(0)
	v_add_f32_e32 v114, v114, v118
	v_add_f32_e32 v116, v116, v119
	ds_bpermute_b32 v118, v136, v114
	ds_bpermute_b32 v119, v136, v116
	s_waitcnt lgkmcnt(0)
	v_add_f32_e32 v114, v114, v118
	v_add_f32_e32 v116, v116, v119
	v_mov_b32_e32 v120, 0x358637bd
	s_mov_b32 s2, 0x3c800000
	v_fma_f32 v114, v114, s2, v120
	v_fma_f32 v116, v116, s2, v120
	v_mul_f32_e32 v118, 0x4b800000, v114
	v_cmp_gt_f32_e32 vcc, s3, v114
	s_nop 1
	v_cndmask_b32_e32 v118, v114, v118, vcc
	v_rsq_f32_e32 v118, v118
	s_nop 0
	v_mul_f32_e32 v122, 0x45800000, v118
	v_cndmask_b32_e32 v122, v118, v122, vcc
	v_mul_f32_e32 v119, 0x4b800000, v116
	v_cmp_gt_f32_e32 vcc, s3, v116
	s_nop 1
	v_cndmask_b32_e32 v119, v116, v119, vcc
	v_rsq_f32_e32 v119, v119
	s_nop 0
	v_mul_f32_e32 v124, 0x45800000, v119
	v_cndmask_b32_e32 v124, v119, v124, vcc
	v_mul_f32_e32 v122, s43, v122
	v_mul_f32_e32 v124, s43, v124
	v_pk_mul_f32 v[126:127], v[194:195], v[122:123] op_sel_hi:[1,0]
	v_pk_mul_f32 v[78:79], v[78:79], v[126:127]
	v_pk_mul_f32 v[126:127], v[196:197], v[122:123] op_sel_hi:[1,0]
	v_pk_mul_f32 v[80:81], v[80:81], v[126:127]
	v_pk_mul_f32 v[126:127], v[198:199], v[122:123] op_sel_hi:[1,0]
	v_pk_mul_f32 v[74:75], v[74:75], v[126:127]
	v_pk_mul_f32 v[126:127], v[200:201], v[122:123] op_sel_hi:[1,0]
	v_pk_mul_f32 v[76:77], v[76:77], v[126:127]
	v_pk_mul_f32 v[126:127], v[202:203], v[122:123] op_sel_hi:[1,0]
	v_pk_mul_f32 v[66:67], v[66:67], v[126:127]
	v_pk_mul_f32 v[126:127], v[204:205], v[122:123] op_sel_hi:[1,0]
	v_pk_mul_f32 v[68:69], v[68:69], v[126:127]
	v_pk_mul_f32 v[126:127], v[206:207], v[122:123] op_sel_hi:[1,0]
	v_pk_mul_f32 v[58:59], v[58:59], v[126:127]
	v_pk_mul_f32 v[126:127], v[208:209], v[122:123] op_sel_hi:[1,0]
	v_pk_mul_f32 v[60:61], v[60:61], v[126:127]
	v_pk_mul_f32 v[126:127], v[194:195], v[124:125] op_sel_hi:[1,0]
	v_pk_mul_f32 v[70:71], v[70:71], v[126:127]
	v_pk_mul_f32 v[126:127], v[196:197], v[124:125] op_sel_hi:[1,0]
	v_pk_mul_f32 v[72:73], v[72:73], v[126:127]
	v_pk_mul_f32 v[126:127], v[198:199], v[124:125] op_sel_hi:[1,0]
	v_pk_mul_f32 v[62:63], v[62:63], v[126:127]
	v_pk_mul_f32 v[126:127], v[200:201], v[124:125] op_sel_hi:[1,0]
	v_pk_mul_f32 v[64:65], v[64:65], v[126:127]
	v_pk_mul_f32 v[126:127], v[202:203], v[124:125] op_sel_hi:[1,0]
	v_pk_mul_f32 v[54:55], v[54:55], v[126:127]
	v_pk_mul_f32 v[126:127], v[204:205], v[124:125] op_sel_hi:[1,0]
	v_pk_mul_f32 v[56:57], v[56:57], v[126:127]
	v_pk_mul_f32 v[126:127], v[206:207], v[124:125] op_sel_hi:[1,0]
	v_pk_mul_f32 v[50:51], v[50:51], v[126:127]
	v_pk_mul_f32 v[126:127], v[208:209], v[124:125] op_sel_hi:[1,0]
	v_pk_mul_f32 v[52:53], v[52:53], v[126:127]
	s_cmp_eq_u32 s42, 0
	s_cbranch_scc1 .Lea_pack_10
	s_waitcnt vmcnt(0)
	v_mul_f32_e32 v126, v74, v211
	v_mul_f32_e32 v127, v78, v211
	v_fma_f32 v78, v78, v210, -v126
	v_fma_f32 v74, v74, v210, v127
	v_mul_f32_e32 v126, v75, v213
	v_mul_f32_e32 v127, v79, v213
	v_fma_f32 v79, v79, v212, -v126
	v_fma_f32 v75, v75, v212, v127
	v_mul_f32_e32 v126, v76, v215
	v_mul_f32_e32 v127, v80, v215
	v_fma_f32 v80, v80, v214, -v126
	v_fma_f32 v76, v76, v214, v127
	v_mul_f32_e32 v126, v77, v217
	v_mul_f32_e32 v127, v81, v217
	v_fma_f32 v81, v81, v216, -v126
	v_fma_f32 v77, v77, v216, v127
	v_mul_f32_e32 v126, v58, v227
	v_mul_f32_e32 v127, v66, v227
	v_fma_f32 v66, v66, v226, -v126
	v_fma_f32 v58, v58, v226, v127
	v_mul_f32_e32 v126, v59, v229
	v_mul_f32_e32 v127, v67, v229
	v_fma_f32 v67, v67, v228, -v126
	v_fma_f32 v59, v59, v228, v127
	v_mul_f32_e32 v126, v60, v231
	v_mul_f32_e32 v127, v68, v231
	v_fma_f32 v68, v68, v230, -v126
	v_fma_f32 v60, v60, v230, v127
	v_mul_f32_e32 v126, v61, v233
	v_mul_f32_e32 v127, v69, v233
	v_fma_f32 v69, v69, v232, -v126
	v_fma_f32 v61, v61, v232, v127
	v_mul_f32_e32 v126, v62, v211
	v_mul_f32_e32 v127, v70, v211
	v_fma_f32 v70, v70, v210, -v126
	v_fma_f32 v62, v62, v210, v127
	v_mul_f32_e32 v126, v63, v213
	v_mul_f32_e32 v127, v71, v213
	v_fma_f32 v71, v71, v212, -v126
	v_fma_f32 v63, v63, v212, v127
	v_mul_f32_e32 v126, v64, v215
	v_mul_f32_e32 v127, v72, v215
	v_fma_f32 v72, v72, v214, -v126
	v_fma_f32 v64, v64, v214, v127
	v_mul_f32_e32 v126, v65, v217
	v_mul_f32_e32 v127, v73, v217
	v_fma_f32 v73, v73, v216, -v126
	v_fma_f32 v65, v65, v216, v127
	v_mul_f32_e32 v126, v50, v235
	v_mul_f32_e32 v127, v54, v235
	v_fma_f32 v54, v54, v234, -v126
	v_fma_f32 v50, v50, v234, v127
	v_mul_f32_e32 v126, v51, v237
	v_mul_f32_e32 v127, v55, v237
	v_fma_f32 v55, v55, v236, -v126
	v_fma_f32 v51, v51, v236, v127
	v_mul_f32_e32 v126, v52, v243
	v_mul_f32_e32 v127, v56, v243
	v_fma_f32 v56, v56, v242, -v126
	v_fma_f32 v52, v52, v242, v127
	v_mul_f32_e32 v126, v53, v245
	v_mul_f32_e32 v127, v57, v245
	v_fma_f32 v57, v57, v244, -v126
	v_fma_f32 v53, v53, v244, v127
	s_branch .Lea_pack_10

; DI void phaseA_tile(const Params& p0, int l, int ft, int mt, char* lds) {
;     ...
;       } else if (kind == 2) {
;         f32x4 gv[4];
; #pragma unroll
;         for (int m = 0; m < 4; ++m) gv[m] = *(const f32x4*)(gain + m * 16 + fq * 4);
; #pragma unroll
;         for (int n = 0; n < 2; ++n) {
;           float ss = 0.f;
; #pragma unroll
;           for (int m = 0; m < 4; ++m)
; #pragma unroll
;             for (int j = 0; j < 4; ++j) ss += v[n][m][j] * v[n][m][j];
;           ss += __shfl_xor(ss, 16);
;           ss += __shfl_xor(ss, 32);
;           const float rn = rsqrtf(ss * (1.f / 64.f) + EPS) * sc;
; #pragma unroll
;           for (int m = 0; m < 4; ++m)
; #pragma unroll
;             for (int j = 0; j < 4; ++j) v[n][m][j] *= rn * gv[m][j];
;         }
;         if (do_rope) {
; #pragma unroll
;           for (int n = 0; n < 2; ++n) {
;             f32x4 cs4[2][2];
;             const int s = s_base + tl[gp * 2 + n];
; #pragma unroll
;             for (int hf = 0; hf < 2; ++hf) {
;               const int pos = hf == 0 ? (s >> 6) : (s & 63);
;               const float* tb = p.rope + (size_t)pos * 32 + fq * 8;
;               cs4[hf][0] = *(const f32x4*)(tb);
;               cs4[hf][1] = *(const f32x4*)(tb + 4);
;             }
; #pragma unroll
;             for (int hf = 0; hf < 2; ++hf)
; #pragma unroll
;               for (int j = 0; j < 4; ++j) {
;                 const float c = cs4[hf][j >> 1][(j & 1) * 2], sn = cs4[hf][j >> 1][(j & 1) * 2 + 1];
;                 const float x1 = v[n][2 * hf][j], x2 = v[n][2 * hf + 1][j];
;                 v[n][2 * hf][j] = x1 * c - x2 * sn;
;                 v[n][2 * hf + 1][j] = x2 * c + x1 * sn;
;               }
;           }
;         }
.Lea_n1_01:
	s_cmp_eq_u32 s40, 2
	s_cbranch_scc0 .Lea_n2_01
	v_pk_mul_f32 v[114:115], v[110:111], v[110:111]
	v_pk_fma_f32 v[114:115], v[112:113], v[112:113], v[114:115]
	v_pk_fma_f32 v[114:115], v[106:107], v[106:107], v[114:115]
	v_pk_fma_f32 v[114:115], v[108:109], v[108:109], v[114:115]
	v_pk_fma_f32 v[114:115], v[98:99], v[98:99], v[114:115]
	v_pk_fma_f32 v[114:115], v[100:101], v[100:101], v[114:115]
	v_pk_fma_f32 v[114:115], v[90:91], v[90:91], v[114:115]
	v_pk_fma_f32 v[114:115], v[92:93], v[92:93], v[114:115]
	v_pk_mul_f32 v[116:117], v[102:103], v[102:103]
	v_pk_fma_f32 v[116:117], v[104:105], v[104:105], v[116:117]
	v_pk_fma_f32 v[116:117], v[94:95], v[94:95], v[116:117]
	v_pk_fma_f32 v[116:117], v[96:97], v[96:97], v[116:117]
	v_pk_fma_f32 v[116:117], v[86:87], v[86:87], v[116:117]
	v_pk_fma_f32 v[116:117], v[88:89], v[88:89], v[116:117]
	v_pk_fma_f32 v[116:117], v[82:83], v[82:83], v[116:117]
	v_pk_fma_f32 v[116:117], v[84:85], v[84:85], v[116:117]
	v_add_f32_e32 v114, v114, v115
	v_add_f32_e32 v116, v116, v117
	ds_bpermute_b32 v118, v135, v114
	ds_bpermute_b32 v119, v135, v116
	s_waitcnt lgkmcnt(0)
	v_add_f32_e32 v114, v114, v118
	v_add_f32_e32 v116, v116, v119
	ds_bpermute_b32 v118, v136, v114
	ds_bpermute_b32 v119, v136, v116
	s_waitcnt lgkmcnt(0)
	v_add_f32_e32 v114, v114, v118
	v_add_f32_e32 v116, v116, v119
	v_mov_b32_e32 v120, 0x358637bd
	s_mov_b32 s2, 0x3c800000
	v_fma_f32 v114, v114, s2, v120
	v_fma_f32 v116, v116, s2, v120
	v_mul_f32_e32 v118, 0x4b800000, v114
	v_cmp_gt_f32_e32 vcc, s3, v114
	s_nop 1
	v_cndmask_b32_e32 v118, v114, v118, vcc
	v_rsq_f32_e32 v118, v118
	s_nop 0
	v_mul_f32_e32 v122, 0x45800000, v118
	v_cndmask_b32_e32 v122, v118, v122, vcc
	v_mul_f32_e32 v119, 0x4b800000, v116
	v_cmp_gt_f32_e32 vcc, s3, v116
	s_nop 1
	v_cndmask_b32_e32 v119, v116, v119, vcc
	v_rsq_f32_e32 v119, v119
	s_nop 0
	v_mul_f32_e32 v124, 0x45800000, v119
	v_cndmask_b32_e32 v124, v119, v124, vcc
	v_mul_f32_e32 v122, s43, v122
	v_mul_f32_e32 v124, s43, v124
	v_pk_mul_f32 v[126:127], v[194:195], v[122:123] op_sel_hi:[1,0]
	v_pk_mul_f32 v[110:111], v[110:111], v[126:127]
	v_pk_mul_f32 v[126:127], v[196:197], v[122:123] op_sel_hi:[1,0]
	v_pk_mul_f32 v[112:113], v[112:113], v[126:127]
	v_pk_mul_f32 v[126:127], v[198:199], v[122:123] op_sel_hi:[1,0]
	v_pk_mul_f32 v[106:107], v[106:107], v[126:127]
	v_pk_mul_f32 v[126:127], v[200:201], v[122:123] op_sel_hi:[1,0]
	v_pk_mul_f32 v[108:109], v[108:109], v[126:127]
	v_pk_mul_f32 v[126:127], v[202:203], v[122:123] op_sel_hi:[1,0]
	v_pk_mul_f32 v[98:99], v[98:99], v[126:127]
	v_pk_mul_f32 v[126:127], v[204:205], v[122:123] op_sel_hi:[1,0]
	v_pk_mul_f32 v[100:101], v[100:101], v[126:127]
	v_pk_mul_f32 v[126:127], v[206:207], v[122:123] op_sel_hi:[1,0]
	v_pk_mul_f32 v[90:91], v[90:91], v[126:127]
	v_pk_mul_f32 v[126:127], v[208:209], v[122:123] op_sel_hi:[1,0]
	v_pk_mul_f32 v[92:93], v[92:93], v[126:127]
	v_pk_mul_f32 v[126:127], v[194:195], v[124:125] op_sel_hi:[1,0]
	v_pk_mul_f32 v[102:103], v[102:103], v[126:127]
	v_pk_mul_f32 v[126:127], v[196:197], v[124:125] op_sel_hi:[1,0]
	v_pk_mul_f32 v[104:105], v[104:105], v[126:127]
	v_pk_mul_f32 v[126:127], v[198:199], v[124:125] op_sel_hi:[1,0]
	v_pk_mul_f32 v[94:95], v[94:95], v[126:127]
	v_pk_mul_f32 v[126:127], v[200:201], v[124:125] op_sel_hi:[1,0]
	v_pk_mul_f32 v[96:97], v[96:97], v[126:127]
	v_pk_mul_f32 v[126:127], v[202:203], v[124:125] op_sel_hi:[1,0]
	v_pk_mul_f32 v[86:87], v[86:87], v[126:127]
	v_pk_mul_f32 v[126:127], v[204:205], v[124:125] op_sel_hi:[1,0]
	v_pk_mul_f32 v[88:89], v[88:89], v[126:127]
	v_pk_mul_f32 v[126:127], v[206:207], v[124:125] op_sel_hi:[1,0]
	v_pk_mul_f32 v[82:83], v[82:83], v[126:127]
	v_pk_mul_f32 v[126:127], v[208:209], v[124:125] op_sel_hi:[1,0]
	v_pk_mul_f32 v[84:85], v[84:85], v[126:127]
	s_cmp_eq_u32 s42, 0
	s_cbranch_scc1 .Lea_pack_01
	s_waitcnt vmcnt(0)
	v_mul_f32_e32 v126, v106, v219
	v_mul_f32_e32 v127, v110, v219
	v_fma_f32 v110, v110, v218, -v126
	v_fma_f32 v106, v106, v218, v127
	v_mul_f32_e32 v126, v107, v221
	v_mul_f32_e32 v127, v111, v221
	v_fma_f32 v111, v111, v220, -v126
	v_fma_f32 v107, v107, v220, v127
	v_mul_f32_e32 v126, v108, v223
	v_mul_f32_e32 v127, v112, v223
	v_fma_f32 v112, v112, v222, -v126
	v_fma_f32 v108, v108, v222, v127
	v_mul_f32_e32 v126, v109, v225
	v_mul_f32_e32 v127, v113, v225
	v_fma_f32 v113, v113, v224, -v126
	v_fma_f32 v109, v109, v224, v127
	v_mul_f32_e32 v126, v90, v227
	v_mul_f32_e32 v127, v98, v227
	v_fma_f32 v98, v98, v226, -v126
	v_fma_f32 v90, v90, v226, v127
	v_mul_f32_e32 v126, v91, v229
	v_mul_f32_e32 v127, v99, v229
	v_fma_f32 v99, v99, v228, -v126
	v_fma_f32 v91, v91, v228, v127
	v_mul_f32_e32 v126, v92, v231
	v_mul_f32_e32 v127, v100, v231
	v_fma_f32 v100, v100, v230, -v126
	v_fma_f32 v92, v92, v230, v127
	v_mul_f32_e32 v126, v93, v233
	v_mul_f32_e32 v127, v101, v233
	v_fma_f32 v101, v101, v232, -v126
	v_fma_f32 v93, v93, v232, v127
	v_mul_f32_e32 v126, v94, v219
	v_mul_f32_e32 v127, v102, v219
	v_fma_f32 v102, v102, v218, -v126
	v_fma_f32 v94, v94, v218, v127
	v_mul_f32_e32 v126, v95, v221
	v_mul_f32_e32 v127, v103, v221
	v_fma_f32 v103, v103, v220, -v126
	v_fma_f32 v95, v95, v220, v127
	v_mul_f32_e32 v126, v96, v223
	v_mul_f32_e32 v127, v104, v223
	v_fma_f32 v104, v104, v222, -v126
	v_fma_f32 v96, v96, v222, v127
	v_mul_f32_e32 v126, v97, v225
	v_mul_f32_e32 v127, v105, v225
	v_fma_f32 v105, v105, v224, -v126
	v_fma_f32 v97, v97, v224, v127
	v_mul_f32_e32 v126, v82, v235
	v_mul_f32_e32 v127, v86, v235
	v_fma_f32 v86, v86, v234, -v126
	v_fma_f32 v82, v82, v234, v127
	v_mul_f32_e32 v126, v83, v237
	v_mul_f32_e32 v127, v87, v237
	v_fma_f32 v87, v87, v236, -v126
	v_fma_f32 v83, v83, v236, v127
	v_mul_f32_e32 v126, v84, v243
	v_mul_f32_e32 v127, v88, v243
	v_fma_f32 v88, v88, v242, -v126
	v_fma_f32 v84, v84, v242, v127
	v_mul_f32_e32 v126, v85, v245
	v_mul_f32_e32 v127, v89, v245
	v_fma_f32 v89, v89, v244, -v126
	v_fma_f32 v85, v85, v244, v127
	s_branch .Lea_pack_01

; DI void phaseA_tile(const Params& p0, int l, int ft, int mt, char* lds) {
;     ...
;       } else if (kind == 2) {
;         f32x4 gv[4];
; #pragma unroll
;         for (int m = 0; m < 4; ++m) gv[m] = *(const f32x4*)(gain + m * 16 + fq * 4);
; #pragma unroll
;         for (int n = 0; n < 2; ++n) {
;           float ss = 0.f;
; #pragma unroll
;           for (int m = 0; m < 4; ++m)
; #pragma unroll
;             for (int j = 0; j < 4; ++j) ss += v[n][m][j] * v[n][m][j];
;           ss += __shfl_xor(ss, 16);
;           ss += __shfl_xor(ss, 32);
;           const float rn = rsqrtf(ss * (1.f / 64.f) + EPS) * sc;
; #pragma unroll
;           for (int m = 0; m < 4; ++m)
; #pragma unroll
;             for (int j = 0; j < 4; ++j) v[n][m][j] *= rn * gv[m][j];
;         }
;         if (do_rope) {
; #pragma unroll
;           for (int n = 0; n < 2; ++n) {
;             f32x4 cs4[2][2];
;             const int s = s_base + tl[gp * 2 + n];
; #pragma unroll
;             for (int hf = 0; hf < 2; ++hf) {
;               const int pos = hf == 0 ? (s >> 6) : (s & 63);
;               const float* tb = p.rope + (size_t)pos * 32 + fq * 8;
;               cs4[hf][0] = *(const f32x4*)(tb);
;               cs4[hf][1] = *(const f32x4*)(tb + 4);
;             }
; #pragma unroll
;             for (int hf = 0; hf < 2; ++hf)
; #pragma unroll
;               for (int j = 0; j < 4; ++j) {
;                 const float c = cs4[hf][j >> 1][(j & 1) * 2], sn = cs4[hf][j >> 1][(j & 1) * 2 + 1];
;                 const float x1 = v[n][2 * hf][j], x2 = v[n][2 * hf + 1][j];
;                 v[n][2 * hf][j] = x1 * c - x2 * sn;
;                 v[n][2 * hf + 1][j] = x2 * c + x1 * sn;
;               }
;           }
;         }
.Lea_n1_11:
	s_cmp_eq_u32 s41, 2
	s_cbranch_scc0 .Lea_n2_11
	v_pk_mul_f32 v[114:115], v[30:31], v[30:31]
	v_pk_fma_f32 v[114:115], v[32:33], v[32:33], v[114:115]
	v_pk_fma_f32 v[114:115], v[26:27], v[26:27], v[114:115]
	v_pk_fma_f32 v[114:115], v[28:29], v[28:29], v[114:115]
	v_pk_fma_f32 v[114:115], v[18:19], v[18:19], v[114:115]
	v_pk_fma_f32 v[114:115], v[20:21], v[20:21], v[114:115]
	v_pk_fma_f32 v[114:115], v[10:11], v[10:11], v[114:115]
	v_pk_fma_f32 v[114:115], v[12:13], v[12:13], v[114:115]
	v_pk_mul_f32 v[116:117], v[22:23], v[22:23]
	v_pk_fma_f32 v[116:117], v[24:25], v[24:25], v[116:117]
	v_pk_fma_f32 v[116:117], v[14:15], v[14:15], v[116:117]
	v_pk_fma_f32 v[116:117], v[16:17], v[16:17], v[116:117]
	v_pk_fma_f32 v[116:117], v[6:7], v[6:7], v[116:117]
	v_pk_fma_f32 v[116:117], v[8:9], v[8:9], v[116:117]
	v_pk_fma_f32 v[116:117], v[2:3], v[2:3], v[116:117]
	v_pk_fma_f32 v[116:117], v[4:5], v[4:5], v[116:117]
	v_add_f32_e32 v114, v114, v115
	v_add_f32_e32 v116, v116, v117
	ds_bpermute_b32 v118, v135, v114
	ds_bpermute_b32 v119, v135, v116
	s_waitcnt lgkmcnt(0)
	v_add_f32_e32 v114, v114, v118
	v_add_f32_e32 v116, v116, v119
	ds_bpermute_b32 v118, v136, v114
	ds_bpermute_b32 v119, v136, v116
	s_waitcnt lgkmcnt(0)
	v_add_f32_e32 v114, v114, v118
	v_add_f32_e32 v116, v116, v119
	v_mov_b32_e32 v120, 0x358637bd
	s_mov_b32 s2, 0x3c800000
	v_fma_f32 v114, v114, s2, v120
	v_fma_f32 v116, v116, s2, v120
	v_mul_f32_e32 v118, 0x4b800000, v114
	v_cmp_gt_f32_e32 vcc, s3, v114
	s_nop 1
	v_cndmask_b32_e32 v118, v114, v118, vcc
	v_rsq_f32_e32 v118, v118
	s_nop 0
	v_mul_f32_e32 v122, 0x45800000, v118
	v_cndmask_b32_e32 v122, v118, v122, vcc
	v_mul_f32_e32 v119, 0x4b800000, v116
	v_cmp_gt_f32_e32 vcc, s3, v116
	s_nop 1
	v_cndmask_b32_e32 v119, v116, v119, vcc
	v_rsq_f32_e32 v119, v119
	s_nop 0
	v_mul_f32_e32 v124, 0x45800000, v119
	v_cndmask_b32_e32 v124, v119, v124, vcc
	v_mul_f32_e32 v122, s43, v122
	v_mul_f32_e32 v124, s43, v124
	v_pk_mul_f32 v[126:127], v[194:195], v[122:123] op_sel_hi:[1,0]
	v_pk_mul_f32 v[30:31], v[30:31], v[126:127]
	v_pk_mul_f32 v[126:127], v[196:197], v[122:123] op_sel_hi:[1,0]
	v_pk_mul_f32 v[32:33], v[32:33], v[126:127]
	v_pk_mul_f32 v[126:127], v[198:199], v[122:123] op_sel_hi:[1,0]
	v_pk_mul_f32 v[26:27], v[26:27], v[126:127]
	v_pk_mul_f32 v[126:127], v[200:201], v[122:123] op_sel_hi:[1,0]
	v_pk_mul_f32 v[28:29], v[28:29], v[126:127]
	v_pk_mul_f32 v[126:127], v[202:203], v[122:123] op_sel_hi:[1,0]
	v_pk_mul_f32 v[18:19], v[18:19], v[126:127]
	v_pk_mul_f32 v[126:127], v[204:205], v[122:123] op_sel_hi:[1,0]
	v_pk_mul_f32 v[20:21], v[20:21], v[126:127]
	v_pk_mul_f32 v[126:127], v[206:207], v[122:123] op_sel_hi:[1,0]
	v_pk_mul_f32 v[10:11], v[10:11], v[126:127]
	v_pk_mul_f32 v[126:127], v[208:209], v[122:123] op_sel_hi:[1,0]
	v_pk_mul_f32 v[12:13], v[12:13], v[126:127]
	v_pk_mul_f32 v[126:127], v[194:195], v[124:125] op_sel_hi:[1,0]
	v_pk_mul_f32 v[22:23], v[22:23], v[126:127]
	v_pk_mul_f32 v[126:127], v[196:197], v[124:125] op_sel_hi:[1,0]
	v_pk_mul_f32 v[24:25], v[24:25], v[126:127]
	v_pk_mul_f32 v[126:127], v[198:199], v[124:125] op_sel_hi:[1,0]
	v_pk_mul_f32 v[14:15], v[14:15], v[126:127]
	v_pk_mul_f32 v[126:127], v[200:201], v[124:125] op_sel_hi:[1,0]
	v_pk_mul_f32 v[16:17], v[16:17], v[126:127]
	v_pk_mul_f32 v[126:127], v[202:203], v[124:125] op_sel_hi:[1,0]
	v_pk_mul_f32 v[6:7], v[6:7], v[126:127]
	v_pk_mul_f32 v[126:127], v[204:205], v[124:125] op_sel_hi:[1,0]
	v_pk_mul_f32 v[8:9], v[8:9], v[126:127]
	v_pk_mul_f32 v[126:127], v[206:207], v[124:125] op_sel_hi:[1,0]
	v_pk_mul_f32 v[2:3], v[2:3], v[126:127]
	v_pk_mul_f32 v[126:127], v[208:209], v[124:125] op_sel_hi:[1,0]
	v_pk_mul_f32 v[4:5], v[4:5], v[126:127]
	s_cmp_eq_u32 s42, 0
	s_cbranch_scc1 .Lea_pack_11
	s_waitcnt vmcnt(0)
	v_mul_f32_e32 v126, v26, v219
	v_mul_f32_e32 v127, v30, v219
	v_fma_f32 v30, v30, v218, -v126
	v_fma_f32 v26, v26, v218, v127
	v_mul_f32_e32 v126, v27, v221
	v_mul_f32_e32 v127, v31, v221
	v_fma_f32 v31, v31, v220, -v126
	v_fma_f32 v27, v27, v220, v127
	v_mul_f32_e32 v126, v28, v223
	v_mul_f32_e32 v127, v32, v223
	v_fma_f32 v32, v32, v222, -v126
	v_fma_f32 v28, v28, v222, v127
	v_mul_f32_e32 v126, v29, v225
	v_mul_f32_e32 v127, v33, v225
	v_fma_f32 v33, v33, v224, -v126
	v_fma_f32 v29, v29, v224, v127
	v_mul_f32_e32 v126, v10, v227
	v_mul_f32_e32 v127, v18, v227
	v_fma_f32 v18, v18, v226, -v126
	v_fma_f32 v10, v10, v226, v127
	v_mul_f32_e32 v126, v11, v229
	v_mul_f32_e32 v127, v19, v229
	v_fma_f32 v19, v19, v228, -v126
	v_fma_f32 v11, v11, v228, v127
	v_mul_f32_e32 v126, v12, v231
	v_mul_f32_e32 v127, v20, v231
	v_fma_f32 v20, v20, v230, -v126
	v_fma_f32 v12, v12, v230, v127
	v_mul_f32_e32 v126, v13, v233
	v_mul_f32_e32 v127, v21, v233
	v_fma_f32 v21, v21, v232, -v126
	v_fma_f32 v13, v13, v232, v127
	v_mul_f32_e32 v126, v14, v219
	v_mul_f32_e32 v127, v22, v219
	v_fma_f32 v22, v22, v218, -v126
	v_fma_f32 v14, v14, v218, v127
	v_mul_f32_e32 v126, v15, v221
	v_mul_f32_e32 v127, v23, v221
	v_fma_f32 v23, v23, v220, -v126
	v_fma_f32 v15, v15, v220, v127
	v_mul_f32_e32 v126, v16, v223
	v_mul_f32_e32 v127, v24, v223
	v_fma_f32 v24, v24, v222, -v126
	v_fma_f32 v16, v16, v222, v127
	v_mul_f32_e32 v126, v17, v225
	v_mul_f32_e32 v127, v25, v225
	v_fma_f32 v25, v25, v224, -v126
	v_fma_f32 v17, v17, v224, v127
	v_mul_f32_e32 v126, v2, v235
	v_mul_f32_e32 v127, v6, v235
	v_fma_f32 v6, v6, v234, -v126
	v_fma_f32 v2, v2, v234, v127
	v_mul_f32_e32 v126, v3, v237
	v_mul_f32_e32 v127, v7, v237
	v_fma_f32 v7, v7, v236, -v126
	v_fma_f32 v3, v3, v236, v127
	v_mul_f32_e32 v126, v4, v243
	v_mul_f32_e32 v127, v8, v243
	v_fma_f32 v8, v8, v242, -v126
	v_fma_f32 v4, v4, v242, v127
	v_mul_f32_e32 v126, v5, v245
	v_mul_f32_e32 v127, v9, v245
	v_fma_f32 v9, v9, v244, -v126
	v_fma_f32 v5, v5, v244, v127
	s_branch .Lea_pack_11

; __global__ void __launch_bounds__(NTHREADS, 2) fwd_kernel(Params p_arg, int ph_begin, int ph_end) {
;   __shared__ __attribute__((aligned(16))) char lds[LDS_BYTES];
	.amdhsa_kernel _Z10fwd_kernel6Paramsii
		.amdhsa_group_segment_fixed_size 156480
		.amdhsa_private_segment_fixed_size 0
		.amdhsa_kernarg_size 512
		.amdhsa_user_sgpr_count 2
		.amdhsa_user_sgpr_dispatch_ptr 0
		.amdhsa_user_sgpr_queue_ptr 0
		.amdhsa_user_sgpr_kernarg_segment_ptr 1
		.amdhsa_user_sgpr_dispatch_id 0
		.amdhsa_user_sgpr_kernarg_preload_length 0
		.amdhsa_user_sgpr_kernarg_preload_offset 0
		.amdhsa_user_sgpr_private_segment_size 0
		.amdhsa_uses_dynamic_stack 0
		.amdhsa_enable_private_segment 0
		.amdhsa_system_sgpr_workgroup_id_x 1
		.amdhsa_system_sgpr_workgroup_id_y 0
		.amdhsa_system_sgpr_workgroup_id_z 0
		.amdhsa_system_sgpr_workgroup_info 0
		.amdhsa_system_vgpr_workitem_id 2
		.amdhsa_next_free_vgpr 256
		.amdhsa_next_free_sgpr 98
		.amdhsa_accum_offset 256
		.amdhsa_reserve_vcc 1
		.amdhsa_float_round_mode_32 0
		.amdhsa_float_round_mode_16_64 0
		.amdhsa_float_denorm_mode_32 3
		.amdhsa_float_denorm_mode_16_64 3
		.amdhsa_dx10_clamp 1
		.amdhsa_ieee_mode 1
		.amdhsa_fp16_overflow 0
		.amdhsa_tg_split 0
		.amdhsa_exception_fp_ieee_invalid_op 0
		.amdhsa_exception_fp_denorm_src 0
		.amdhsa_exception_fp_ieee_div_zero 0
		.amdhsa_exception_fp_ieee_overflow 0
		.amdhsa_exception_fp_ieee_underflow 0
		.amdhsa_exception_fp_ieee_inexact 0
		.amdhsa_exception_int_div_zero 0
	.end_amdhsa_kernel

; __global__ void __launch_bounds__(NTHREADS, 2) fwd_kernel(Params p_arg, int ph_begin, int ph_end) {
;   __shared__ __attribute__((aligned(16))) char lds[LDS_BYTES];
amdhsa.kernels:
  - .agpr_count:     0
    .args:
      - .offset:         0
        .size:           248
        .value_kind:     by_value
      - .offset:         248
        .size:           4
        .value_kind:     by_value
      - .offset:         252
        .size:           4
        .value_kind:     by_value
      - .offset:         256
        .size:           4
        .value_kind:     hidden_block_count_x
      - .offset:         260
        .size:           4
        .value_kind:     hidden_block_count_y
      - .offset:         264
        .size:           4
        .value_kind:     hidden_block_count_z
      - .offset:         268
        .size:           2
        .value_kind:     hidden_group_size_x
      - .offset:         270
        .size:           2
        .value_kind:     hidden_group_size_y
      - .offset:         272
        .size:           2
        .value_kind:     hidden_group_size_z
      - .offset:         274
        .size:           2
        .value_kind:     hidden_remainder_x
      - .offset:         276
        .size:           2
        .value_kind:     hidden_remainder_y
      - .offset:         278
        .size:           2
        .value_kind:     hidden_remainder_z
      - .offset:         296
        .size:           8
        .value_kind:     hidden_global_offset_x
      - .offset:         304
        .size:           8
        .value_kind:     hidden_global_offset_y
      - .offset:         312
        .size:           8
        .value_kind:     hidden_global_offset_z
      - .offset:         320
        .size:           2
        .value_kind:     hidden_grid_dims
      - .offset:         344
        .size:           8
        .value_kind:     hidden_multigrid_sync_arg
    .group_segment_fixed_size: 156480
    .kernarg_segment_align: 8
    .kernarg_segment_size: 512
    .language:       OpenCL C
    .language_version:
      - 2
      - 0
    .max_flat_workgroup_size: 512
    .name:           _Z10fwd_kernel6Paramsii
    .private_segment_fixed_size: 0
    .sgpr_count:     104
    .sgpr_spill_count: 87
    .symbol:         _Z10fwd_kernel6Paramsii.kd
    .uniform_work_group_size: 1
    .uses_dynamic_stack: false
    .vgpr_count:     256
    .vgpr_spill_count: 0
    .wavefront_size: 64
